# v31 + cross-group phase order: rows_h(g+1) right after FFN-up(g) with no barrier, one barrier, FFN-down(g) flows into in-proj(g+1): one grid barrier less per group transition
# baseline (speedup 1.0000x reference)
; __device__ __forceinline__ char* opaque(char* q) { size_t z = 0; asm volatile("" : "+s"(z)); return q + z; }
; __device__ __forceinline__ Grp make_grp(const Params& p, int g) {
;   Grp G; if (g == 0) { G.x = p.x_prompt; G.out = p.out; G.nseq = 2; G.Ls = 8192; }
;   else { G.x = p.x_sample + (size_t)(g - 1) * NREAL * DM; G.out = p.out + (size_t)g * NREAL * DM; G.nseq = 1; G.Ls = 16384; }
;   G.RG = NREAL + 256 * G.nseq; return G;
; }
; __global__ void __launch_bounds__(NTHR, 2) mega(Params p) {
;     ...
;   for (int step = 0; step < 3 * NSTP; ++step) {
;     const int g = step / NSTP; int ph = step % NSTP;
;     ...
;     ph -= (ph > PROBE_AT) ? 1 : 0;
;     ...
;     char* ws = opaque(p.ws);
;     const Grp G = make_grp(p, g);
;     bool is_gemm = false, sync_after = true;
;     Gemm gm{nullptr, nullptr, 1024, 1024, NREAL, 1024, 1024, nullptr, nullptr, 0};
;     EpiGen E{0, 0, nullptr, nullptr, nullptr, nullptr, nullptr, nullptr};
;     switch (ph) {
.LBB0_224:
	s_and_b32 s2, s55, 0xff
	s_cmp_eq_u32 s2, 16
	s_cselect_b32 s3, 1, 0
	s_cmp_eq_u32 s2, 33
	s_cselect_b32 s12, 1, 0
	s_or_b32 s3, s3, s12
	s_cmp_eq_u32 s2, 17
	s_cselect_b32 s12, 1, 0
	s_sub_i32 s3, s3, s12
	s_cmp_eq_u32 s2, 34
	s_cselect_b32 s12, 1, 0
	s_sub_i32 s3, s3, s12
	s_add_i32 s2, s2, s3
	s_mov_b32 s12, s2
	s_mulk_i32 s2, 0xf1
	s_lshr_b32 s2, s2, 12
	s_mul_i32 s3, s2, 17
	s_mov_b64 s[0:1], 0
	s_sub_i32 s12, s12, s3
	s_add_u32 s20, s80, s0
	v_readlane_b32 s60, v253, 3
	s_addc_u32 s21, s81, s1
	v_readlane_b32 s61, v253, 4
	s_cmp_eq_u32 s2, 0
	v_readlane_b32 s62, v253, 5
	v_readlane_b32 s63, v253, 6
	v_readlane_b32 s64, v253, 7
	v_readlane_b32 s65, v253, 8
	s_mov_b64 s[36:37], s[60:61]
	s_cselect_b64 s[88:89], -1, 0
	s_lshl_b32 s2, s2, 26
	s_mov_b64 s[38:39], s[62:63]
	s_add_u32 s0, s38, s2
	s_addc_u32 s1, s39, 0
	v_readlane_b32 s66, v253, 9
	v_readlane_b32 s67, v253, 10
	v_readlane_b32 s68, v253, 11
	v_readlane_b32 s69, v253, 12
	v_readlane_b32 s70, v253, 13
	v_readlane_b32 s71, v253, 14
	v_readlane_b32 s72, v253, 15
	v_readlane_b32 s73, v253, 16
	v_readlane_b32 s74, v253, 17
	v_readlane_b32 s75, v253, 18
	s_add_u32 s24, s0, 0xfc000000
	s_mov_b64 s[40:41], s[64:65]
	s_addc_u32 s25, s1, -1
	v_readlane_b32 s60, v254, 38
	s_and_b64 s[0:1], s[88:89], exec
	v_readlane_b32 s74, v254, 52
	v_readlane_b32 s75, v254, 53
	s_cselect_b32 s2, 0, s2
	s_mov_b64 s[26:27], s[74:75]
	s_cselect_b32 s3, 0, 0
	s_add_u32 s34, s26, s2
	s_addc_u32 s35, s27, s3
	s_and_b64 s[0:1], s[88:89], exec
	s_cselect_b32 s1, s37, s25
	s_cselect_b32 s0, s36, s24
	v_writelane_b32 v255, s0, 23
	v_readlane_b32 s61, v254, 39
	v_readlane_b32 s62, v254, 40
	v_writelane_b32 v255, s1, 24
	s_movk_i32 s0, 0x2000
	s_cselect_b32 s48, s0, 0x4000
	s_and_b32 s49, s12, 0xff
	v_readlane_b32 s63, v254, 41
	v_readlane_b32 s64, v254, 42
	v_readlane_b32 s65, v254, 43
	v_readlane_b32 s66, v254, 44
	v_readlane_b32 s67, v254, 45
	v_readlane_b32 s68, v254, 46
	v_readlane_b32 s69, v254, 47
	v_readlane_b32 s70, v254, 48
	v_readlane_b32 s71, v254, 49
	s_cmp_lt_i32 s49, 8
	s_mov_b64 s[26:27], -1
	s_movk_i32 s91, 0x3fff
	v_readlane_b32 s72, v254, 50
	v_readlane_b32 s73, v254, 51
	s_cbranch_scc1 .LBB0_417
	s_and_b32 s50, 0xffff, s49
	s_cmp_lt_i32 s50, 12
	s_cbranch_scc1 .LBB0_244
	s_mov_b64 s[36:37], -1
	s_cmp_lt_i32 s50, 14
	s_mov_b64 s[24:25], -1
	s_cbranch_scc1 .LBB0_238
	s_mov_b64 s[0:1], -1
	s_cmp_lt_i32 s50, 15
	s_cbranch_scc1 .LBB0_232
	s_cmp_lg_u32 s50, 15
	s_cbranch_scc0 .LBB0_230
	s_add_u32 s60, s20, 0x8640000
	s_addc_u32 s61, s21, 0
	s_add_u32 s62, s20, 0x20c0000
	s_addc_u32 s63, s21, 0
	s_mov_b64 s[24:25], 0

; __device__ __forceinline__ void xcd_barrier(const XcdBarrier& b) {
;   asm volatile("s_waitcnt vmcnt(0)" ::: "memory");
;   __syncthreads();
;   if (threadIdx.x == 0) {
;     unsigned* bar = b.bar;
;     __builtin_amdgcn_s_waitcnt(0);
;     unsigned nloc = b.st[0], nx = b.st[1];
;     if (nloc == 0u) { xcd_barrier_complete(bar, b.x, nloc, nx); b.st[0] = nloc; b.st[1] = nx; }
; __global__ void __launch_bounds__(NTHR, 2) mega(Params p) {
;     ...
;     if (is_gemm) gemm_phase(lds, gm, E);
;     if (sync_after) xcd_barrier(xb);
.LBB0_1255:
	v_readlane_b32 s64, v254, 38
	v_readlane_b32 s0, v255, 25
	v_readlane_b32 s65, v254, 39
	v_readlane_b32 s66, v254, 40
	v_readlane_b32 s67, v254, 41
	v_readlane_b32 s68, v254, 42
	v_readlane_b32 s69, v254, 43
	v_readlane_b32 s70, v254, 44
	v_readlane_b32 s71, v254, 45
	v_readlane_b32 s72, v254, 46
	v_readlane_b32 s73, v254, 47
	v_readlane_b32 s74, v254, 48
	v_readlane_b32 s75, v254, 49
	v_readlane_b32 s1, v255, 26
	v_readlane_b32 s38, v254, 55
	v_readlane_b32 s40, v254, 57
	v_readlane_b32 s42, v254, 59
	v_readlane_b32 s48, v254, 61
	v_readlane_b32 s50, v254, 63
	v_readlane_b32 s52, v255, 1
	v_readlane_b32 s58, v255, 3
	v_readlane_b32 s60, v255, 5
	v_readlane_b32 s62, v255, 7
	v_readlane_b32 s64, v255, 9
	v_readlane_b32 s66, v255, 11
	v_readlane_b32 s68, v255, 13
	v_readlane_b32 s70, v255, 15
	v_readlane_b32 s72, v255, 17
	v_readlane_b32 s74, v255, 19
	v_readlane_b32 s28, v255, 21
	s_andn2_b64 vcc, exec, s[0:1]
	v_readlane_b32 s90, v254, 36
	v_readlane_b32 s36, v254, 54
	v_readlane_b32 s39, v254, 56
	v_readlane_b32 s41, v254, 58
	v_readlane_b32 s43, v254, 60
	v_readlane_b32 s49, v254, 62
	v_readlane_b32 s51, v255, 0
	v_readlane_b32 s53, v255, 2
	v_readlane_b32 s59, v255, 4
	v_readlane_b32 s61, v255, 6
	v_readlane_b32 s63, v255, 8
	v_readlane_b32 s65, v255, 10
	v_readlane_b32 s67, v255, 12
	v_readlane_b32 s69, v255, 14
	v_readlane_b32 s71, v255, 16
	v_readlane_b32 s73, v255, 18
	v_readlane_b32 s75, v255, 20
	v_readlane_b32 s29, v255, 22
	v_readlane_b32 s76, v254, 50
	v_readlane_b32 s77, v254, 51
	v_readlane_b32 s78, v254, 52
	v_readlane_b32 s79, v254, 53
	v_readlane_b32 s91, v254, 37
	s_cmp_eq_u32 s55, 15
	s_cbranch_scc1 .LBB0_223
	s_cmp_eq_u32 s55, 32
	s_cbranch_scc1 .LBB0_223
	s_cmp_eq_u32 s55, 17
	s_cbranch_scc1 .LBB0_223
	s_cmp_eq_u32 s55, 34
	s_cbranch_scc1 .LBB0_223
	s_cmp_eq_u32 s55, 50
	s_cbranch_scc1 .LBB0_223
	s_cbranch_vccnz .LBB0_223
	s_waitcnt vmcnt(0)
	s_waitcnt vmcnt(0) lgkmcnt(0)
	s_barrier
	s_mov_b64 s[0:1], exec
	v_readlane_b32 s2, v253, 1
	v_readlane_b32 s3, v253, 2
	s_and_b64 s[2:3], s[0:1], s[2:3]
	s_mov_b64 exec, s[2:3]
	s_cbranch_execz .LBB0_222
	v_readlane_b32 s2, v254, 34
	s_waitcnt vmcnt(0) expcnt(0) lgkmcnt(0)
	s_nop 0
	v_mov_b32_e32 v0, s2
	ds_read_b32 v2, v0
	v_readlane_b32 s2, v254, 35
	s_waitcnt lgkmcnt(0)
	v_cmp_ne_u32_e32 vcc, 0, v2
	v_mov_b32_e32 v0, s2
	ds_read_b32 v0, v0
	s_cbranch_vccnz .LBB0_1272
	s_mov_b32 s12, 1
	s_branch .LBB0_1260
